# fused final epilogue: redundant per-wave agent-scope L1/L2 invalidate after the row-panel counter spin dropped (the following loads are a read-only input and sc1 loads)
# speedup vs baseline: 1.0311x; 1.0122x over previous
.LBB0_1515:
	v_lshlrev_b64 v[74:75], 2, v[184:185]
	v_lshl_add_u64 v[0:1], s[46:47], 0, v[74:75]
	global_load_dwordx4 v[12:15], v[0:1], off
	global_load_dwordx4 v[8:11], v[0:1], off offset:64
	global_load_dwordx4 v[4:7], v[0:1], off offset:512
	s_nop 0
	global_load_dwordx4 v[0:3], v[0:1], off offset:576
	s_nop 0
	global_load_dword v88, v[186:187], off sc1
	global_load_dword v89, v[186:187], off offset:64 sc1
	global_load_dword v90, v[186:187], off offset:128 sc1
	global_load_dword v91, v[186:187], off offset:192 sc1
	v_lshl_add_u64 v[78:79], s[72:73], 0, v[182:183]
	v_lshl_add_u64 v[82:83], s[72:73], 0, v[180:181]
	global_load_dword v181, v[186:187], off offset:512 sc1
	global_load_dword v182, v[186:187], off offset:576 sc1
	global_load_dword v183, v[186:187], off offset:640 sc1
	global_load_dword v185, v[186:187], off offset:704 sc1
	v_mov_b32_e32 v184, 0x358637bd
	v_lshl_add_u64 v[86:87], s[72:73], 0, v[178:179]
	v_lshl_add_u64 v[178:179], v[86:87], 0, v[74:75]
	v_lshl_add_u64 v[78:79], v[78:79], 0, v[74:75]
	v_lshl_add_u64 v[82:83], v[82:83], 0, v[74:75]
	s_waitcnt vmcnt(7)
	v_fmamk_f32 v86, v88, 0x3a800000, v184
	s_waitcnt vmcnt(6)
	v_fmamk_f32 v87, v89, 0x3a800000, v184
	s_waitcnt vmcnt(5)
	v_fmamk_f32 v89, v90, 0x3a800000, v184
	v_rsq_f32_e32 v86, v86
	s_waitcnt vmcnt(4)
	v_fmamk_f32 v91, v91, 0x3a800000, v184
	v_rsq_f32_e32 v88, v87
	v_rsq_f32_e32 v90, v89
	v_rsq_f32_e32 v180, v91
	v_pk_mul_f32 v[92:93], v[124:125], v[86:87] op_sel_hi:[1,0]
	v_pk_mul_f32 v[94:95], v[126:127], v[86:87] op_sel_hi:[1,0]
	v_pk_mul_f32 v[96:97], v[120:121], v[86:87] op_sel_hi:[1,0]
	v_pk_mul_f32 v[98:99], v[122:123], v[86:87] op_sel_hi:[1,0]
	v_pk_mul_f32 v[100:101], v[116:117], v[86:87] op_sel_hi:[1,0]
	v_pk_mul_f32 v[102:103], v[118:119], v[86:87] op_sel_hi:[1,0]
	v_pk_mul_f32 v[104:105], v[112:113], v[86:87] op_sel_hi:[1,0]
	v_pk_mul_f32 v[106:107], v[114:115], v[86:87] op_sel_hi:[1,0]
	v_pk_mul_f32 v[108:109], v[172:173], v[88:89] op_sel_hi:[1,0]
	v_pk_mul_f32 v[110:111], v[174:175], v[88:89] op_sel_hi:[1,0]
	v_pk_mul_f32 v[112:113], v[168:169], v[88:89] op_sel_hi:[1,0]
	v_pk_mul_f32 v[114:115], v[170:171], v[88:89] op_sel_hi:[1,0]
	v_pk_mul_f32 v[116:117], v[164:165], v[88:89] op_sel_hi:[1,0]
	v_pk_mul_f32 v[118:119], v[166:167], v[88:89] op_sel_hi:[1,0]
	v_pk_mul_f32 v[120:121], v[160:161], v[88:89] op_sel_hi:[1,0]
	v_pk_mul_f32 v[122:123], v[162:163], v[88:89] op_sel_hi:[1,0]
	v_pk_mul_f32 v[124:125], v[156:157], v[90:91] op_sel_hi:[1,0]
	v_pk_mul_f32 v[126:127], v[158:159], v[90:91] op_sel_hi:[1,0]
	v_pk_mul_f32 v[152:153], v[152:153], v[90:91] op_sel_hi:[1,0]
	v_pk_mul_f32 v[154:155], v[154:155], v[90:91] op_sel_hi:[1,0]
	v_pk_mul_f32 v[148:149], v[148:149], v[90:91] op_sel_hi:[1,0]
	v_pk_mul_f32 v[150:151], v[150:151], v[90:91] op_sel_hi:[1,0]
	v_pk_mul_f32 v[156:157], v[194:195], v[90:91] op_sel_hi:[1,0]
	v_pk_mul_f32 v[158:159], v[190:191], v[90:91] op_sel_hi:[1,0]
	v_pk_mul_f32 v[88:89], v[14:15], v[94:95]
	v_pk_mul_f32 v[86:87], v[12:13], v[92:93]
	v_pk_mul_f32 v[92:93], v[10:11], v[98:99]
	v_pk_mul_f32 v[90:91], v[8:9], v[96:97]
	v_pk_mul_f32 v[96:97], v[6:7], v[102:103]
	v_pk_mul_f32 v[94:95], v[4:5], v[100:101]
	v_pk_mul_f32 v[100:101], v[2:3], v[106:107]
	v_pk_mul_f32 v[98:99], v[0:1], v[104:105]
	v_pk_mul_f32 v[104:105], v[14:15], v[110:111]
	v_pk_mul_f32 v[102:103], v[12:13], v[108:109]
	v_pk_mul_f32 v[108:109], v[10:11], v[114:115]
	v_pk_mul_f32 v[106:107], v[8:9], v[112:113]
	v_pk_mul_f32 v[112:113], v[6:7], v[118:119]
	v_pk_mul_f32 v[110:111], v[4:5], v[116:117]
	v_pk_mul_f32 v[116:117], v[2:3], v[122:123]
	v_pk_mul_f32 v[114:115], v[0:1], v[120:121]
	v_pk_mul_f32 v[120:121], v[14:15], v[126:127]
	v_pk_mul_f32 v[118:119], v[12:13], v[124:125]
	v_pk_mul_f32 v[124:125], v[10:11], v[154:155]
	v_pk_mul_f32 v[122:123], v[8:9], v[152:153]
	v_pk_mul_f32 v[150:151], v[6:7], v[150:151]
	v_pk_mul_f32 v[148:149], v[4:5], v[148:149]
	v_pk_mul_f32 v[154:155], v[2:3], v[158:159]
	v_pk_mul_f32 v[152:153], v[0:1], v[156:157]
	global_store_dwordx4 v[78:79], v[86:89], off nt
	global_store_dwordx4 v[78:79], v[90:93], off offset:64 nt
	global_store_dwordx4 v[78:79], v[94:97], off offset:512 nt
	global_store_dwordx4 v[78:79], v[98:101], off offset:576 nt
	global_store_dwordx4 v[82:83], v[102:105], off nt
	global_store_dwordx4 v[82:83], v[106:109], off offset:64 nt
	global_store_dwordx4 v[82:83], v[110:113], off offset:512 nt
	global_store_dwordx4 v[82:83], v[114:117], off offset:576 nt
	global_store_dwordx4 v[178:179], v[118:121], off nt
	global_store_dwordx4 v[178:179], v[122:125], off offset:64 nt
	global_store_dwordx4 v[178:179], v[148:151], off offset:512 nt
	global_store_dwordx4 v[178:179], v[152:155], off offset:576 nt
	s_waitcnt vmcnt(15)
	v_pk_mul_f32 v[78:79], v[140:141], v[180:181] op_sel_hi:[1,0]
	v_pk_mul_f32 v[82:83], v[142:143], v[180:181] op_sel_hi:[1,0]
	v_pk_mul_f32 v[86:87], v[12:13], v[78:79]
	v_lshl_add_u64 v[78:79], s[72:73], 0, v[176:177]
	v_pk_mul_f32 v[88:89], v[14:15], v[82:83]
	v_lshl_add_u64 v[78:79], v[78:79], 0, v[74:75]
	global_store_dwordx4 v[78:79], v[86:89], off nt
	v_pk_mul_f32 v[82:83], v[136:137], v[180:181] op_sel_hi:[1,0]
	s_nop 0
	v_pk_mul_f32 v[86:87], v[138:139], v[180:181] op_sel_hi:[1,0]
	s_nop 0
	v_pk_mul_f32 v[88:89], v[10:11], v[86:87]
	v_pk_mul_f32 v[86:87], v[8:9], v[82:83]
	global_store_dwordx4 v[78:79], v[86:89], off offset:64 nt
	v_pk_mul_f32 v[82:83], v[146:147], v[180:181] op_sel_hi:[1,0]
	s_nop 0
	v_pk_mul_f32 v[86:87], v[134:135], v[180:181] op_sel_hi:[1,0]
	s_nop 0
	v_pk_mul_f32 v[88:89], v[6:7], v[86:87]
	v_pk_mul_f32 v[86:87], v[4:5], v[82:83]
	global_store_dwordx4 v[78:79], v[86:89], off offset:512 nt
	v_pk_mul_f32 v[82:83], v[188:189], v[180:181] op_sel_hi:[1,0]
	s_nop 0
	v_fmamk_f32 v88, v181, 0x3a800000, v184
	v_rsq_f32_e32 v90, v88
	v_pk_mul_f32 v[86:87], v[144:145], v[180:181] op_sel_hi:[1,0]
	v_pk_mul_f32 v[52:53], v[52:53], v[90:91] op_sel_hi:[1,0]
	v_pk_mul_f32 v[88:89], v[2:3], v[86:87]
	v_pk_mul_f32 v[86:87], v[0:1], v[82:83]
	global_store_dwordx4 v[78:79], v[86:89], off offset:576 nt
	v_lshl_add_u64 v[78:79], s[72:73], 0, v[192:193]
	v_pk_mul_f32 v[54:55], v[54:55], v[90:91] op_sel_hi:[1,0]
	v_lshl_add_u64 v[78:79], v[78:79], 0, v[74:75]
	v_pk_mul_f32 v[54:55], v[6:7], v[54:55]
	v_pk_mul_f32 v[52:53], v[4:5], v[52:53]
	global_store_dwordx4 v[78:79], v[52:55], off offset:512 nt
	v_pk_mul_f32 v[48:49], v[48:49], v[90:91] op_sel_hi:[1,0]
	v_pk_mul_f32 v[50:51], v[50:51], v[90:91] op_sel_hi:[1,0]
	s_waitcnt vmcnt(19)
	v_fmamk_f32 v52, v182, 0x3a800000, v184
	v_rsq_f32_e32 v52, v52
	v_pk_mul_f32 v[50:51], v[2:3], v[50:51]
	v_pk_mul_f32 v[48:49], v[0:1], v[48:49]
	global_store_dwordx4 v[78:79], v[48:51], off offset:576 nt
	v_pk_mul_f32 v[36:37], v[36:37], v[52:53] op_sel_hi:[1,0]
	v_pk_mul_f32 v[38:39], v[38:39], v[52:53] op_sel_hi:[1,0]
	v_lshl_add_u64 v[48:49], s[72:73], 0, v[132:133]
	v_lshl_add_u64 v[48:49], v[48:49], 0, v[74:75]
	v_pk_mul_f32 v[38:39], v[6:7], v[38:39]
	v_pk_mul_f32 v[36:37], v[4:5], v[36:37]
	global_store_dwordx4 v[48:49], v[36:39], off offset:512 nt
	v_pk_mul_f32 v[28:29], v[28:29], v[52:53] op_sel_hi:[1,0]
	v_pk_mul_f32 v[30:31], v[30:31], v[52:53] op_sel_hi:[1,0]
	s_waitcnt vmcnt(20)
	v_fmamk_f32 v36, v183, 0x3a800000, v184
	v_rsq_f32_e32 v36, v36
	v_pk_mul_f32 v[30:31], v[2:3], v[30:31]
	v_pk_mul_f32 v[28:29], v[0:1], v[28:29]
	v_pk_mul_f32 v[56:57], v[56:57], v[90:91] op_sel_hi:[1,0]
	v_pk_mul_f32 v[58:59], v[58:59], v[90:91] op_sel_hi:[1,0]
	v_pk_mul_f32 v[40:41], v[40:41], v[52:53] op_sel_hi:[1,0]
	v_pk_mul_f32 v[42:43], v[42:43], v[52:53] op_sel_hi:[1,0]
	global_store_dwordx4 v[48:49], v[28:31], off offset:576 nt
	v_pk_mul_f32 v[24:25], v[24:25], v[36:37] op_sel_hi:[1,0]
	v_pk_mul_f32 v[26:27], v[26:27], v[36:37] op_sel_hi:[1,0]
	v_pk_mul_f32 v[28:29], v[32:33], v[36:37] op_sel_hi:[1,0]
	v_lshl_add_u64 v[32:33], s[72:73], 0, v[130:131]
	v_pk_mul_f32 v[58:59], v[10:11], v[58:59]
	v_pk_mul_f32 v[56:57], v[8:9], v[56:57]
	v_pk_mul_f32 v[42:43], v[10:11], v[42:43]
	v_pk_mul_f32 v[40:41], v[8:9], v[40:41]
	v_lshl_add_u64 v[32:33], v[32:33], 0, v[74:75]
	v_pk_mul_f32 v[26:27], v[10:11], v[26:27]
	v_pk_mul_f32 v[24:25], v[8:9], v[24:25]
	global_store_dwordx4 v[78:79], v[56:59], off offset:64 nt
	global_store_dwordx4 v[48:49], v[40:43], off offset:64 nt
	global_store_dwordx4 v[32:33], v[24:27], off offset:64 nt
	v_pk_mul_f32 v[22:23], v[22:23], v[36:37] op_sel_hi:[1,0]
	s_waitcnt vmcnt(23)
	v_fmac_f32_e32 v184, 0x3a800000, v185
	v_pk_mul_f32 v[26:27], v[84:85], v[36:37] op_sel_hi:[1,0]
	v_pk_mul_f32 v[24:25], v[6:7], v[22:23]
	v_pk_mul_f32 v[22:23], v[4:5], v[26:27]
	v_rsq_f32_e32 v26, v184
	global_store_dwordx4 v[32:33], v[22:25], off offset:512 nt
	v_pk_mul_f32 v[20:21], v[20:21], v[36:37] op_sel_hi:[1,0]
	v_pk_mul_f32 v[62:63], v[62:63], v[90:91] op_sel_hi:[1,0]
	v_pk_mul_f32 v[24:25], v[80:81], v[36:37] op_sel_hi:[1,0]
	v_pk_mul_f32 v[46:47], v[46:47], v[52:53] op_sel_hi:[1,0]
	v_pk_mul_f32 v[30:31], v[34:35], v[36:37] op_sel_hi:[1,0]
	v_pk_mul_f32 v[22:23], v[2:3], v[20:21]
	v_pk_mul_f32 v[20:21], v[0:1], v[24:25]
	v_pk_mul_f32 v[18:19], v[18:19], v[26:27] op_sel_hi:[1,0]
	v_pk_mul_f32 v[60:61], v[60:61], v[90:91] op_sel_hi:[1,0]
	v_pk_mul_f32 v[62:63], v[14:15], v[62:63]
	v_pk_mul_f32 v[44:45], v[44:45], v[52:53] op_sel_hi:[1,0]
	v_pk_mul_f32 v[46:47], v[14:15], v[46:47]
	v_pk_mul_f32 v[30:31], v[14:15], v[30:31]
	global_store_dwordx4 v[32:33], v[20:23], off offset:576 nt
	v_pk_mul_f32 v[14:15], v[14:15], v[18:19]
	v_lshl_add_u64 v[18:19], s[72:73], 0, v[128:129]
	v_pk_mul_f32 v[20:21], v[76:77], v[26:27] op_sel_hi:[1,0]
	v_pk_mul_f32 v[60:61], v[12:13], v[60:61]
	v_pk_mul_f32 v[44:45], v[12:13], v[44:45]
	v_pk_mul_f32 v[28:29], v[12:13], v[28:29]
	v_pk_mul_f32 v[12:13], v[12:13], v[20:21]
	v_lshl_add_u64 v[18:19], v[18:19], 0, v[74:75]
	global_store_dwordx4 v[78:79], v[60:63], off nt
	global_store_dwordx4 v[48:49], v[44:47], off nt
	global_store_dwordx4 v[32:33], v[28:31], off nt
	global_store_dwordx4 v[18:19], v[12:15], off nt
	s_nop 1
	v_pk_mul_f32 v[12:13], v[72:73], v[26:27] op_sel_hi:[1,0]
	v_pk_mul_f32 v[14:15], v[16:17], v[26:27] op_sel_hi:[1,0]
	v_pk_mul_f32 v[8:9], v[8:9], v[12:13]
	v_pk_mul_f32 v[10:11], v[10:11], v[14:15]
	global_store_dwordx4 v[18:19], v[8:11], off offset:64 nt
	s_nop 1
	v_pk_mul_f32 v[8:9], v[68:69], v[26:27] op_sel_hi:[1,0]
	v_pk_mul_f32 v[10:11], v[70:71], v[26:27] op_sel_hi:[1,0]
	v_pk_mul_f32 v[4:5], v[4:5], v[8:9]
	v_pk_mul_f32 v[6:7], v[6:7], v[10:11]
	global_store_dwordx4 v[18:19], v[4:7], off offset:512 nt
	s_nop 1
	v_pk_mul_f32 v[4:5], v[64:65], v[26:27] op_sel_hi:[1,0]
	v_pk_mul_f32 v[6:7], v[66:67], v[26:27] op_sel_hi:[1,0]
	v_pk_mul_f32 v[0:1], v[0:1], v[4:5]
	v_pk_mul_f32 v[2:3], v[2:3], v[6:7]
	global_store_dwordx4 v[18:19], v[0:3], off offset:576 nt
